# P0: next row pair prefetched one iteration ahead (issued after the dot block)
# baseline (speedup 1.0000x reference)
.LBB0_35:
	s_or_b64 exec, exec, s[0:1]
	s_add_u32 s0, s66, 0x800000
	s_addc_u32 s1, s67, 0
	v_writelane_b32 v253, s0, 35
	s_cmp_lt_i32 s80, 0xc000
	s_cselect_b64 s[92:93], -1, 0
	v_writelane_b32 v253, s1, 36
	s_cmp_gt_i32 s80, 0xbfff
	v_xor_b32_e32 v245, 1, v174
	v_and_b32_e32 v246, 64, v174
	v_xor_b32_e32 v244, 2, v174
	v_xor_b32_e32 v243, 4, v174
	v_xor_b32_e32 v242, 8, v174
	v_xor_b32_e32 v241, 16, v174
	v_xor_b32_e32 v240, 32, v174
	s_waitcnt lgkmcnt(0)
	s_barrier
	s_cbranch_scc1 .LBB0_40
	v_bfrev_b32_e32 v1, v2
	v_lshrrev_b32_e32 v1, 26, v1
	v_readlane_b32 s16, v253, 0
	v_and_b32_e32 v4, 60, v1
	v_readlane_b32 s26, v253, 10
	v_readlane_b32 s27, v253, 11
	v_readlane_b32 s0, v253, 35
	v_mov_b32_e32 v5, 0
	v_readlane_b32 s1, v253, 36
	v_ashrrev_i32_e32 v3, 31, v2
	v_readlane_b32 s20, v253, 4
	global_load_dword v1, v4, s[26:27]
	v_lshl_add_u64 v[38:39], s[0:1], 0, v[4:5]
	v_lshl_add_u64 v[4:5], v[2:3], 3, s[66:67]
	s_mov_b64 s[0:1], 0x19400000
	v_lshl_add_u64 v[40:41], v[4:5], 0, s[0:1]
	v_and_b32_e32 v4, 1, v2
	v_cmp_eq_u32_e32 vcc, 0, v4
	v_add_u32_e32 v4, 64, v246
	v_cmp_lt_i32_e64 s[0:1], v245, v4
	v_cmp_lt_i32_e64 s[4:5], v244, v4
	v_cmp_lt_i32_e64 s[6:7], v242, v4
	v_cndmask_b32_e64 v5, v174, v245, s[0:1]
	v_lshlrev_b32_e32 v46, 2, v5
	v_and_b32_e32 v5, 2, v2
	v_cmp_eq_u32_e64 s[0:1], 0, v5
	v_cndmask_b32_e64 v5, v174, v244, s[4:5]
	v_lshlrev_b32_e32 v47, 2, v5
	v_and_b32_e32 v5, 4, v2
	v_cmp_lt_i32_e64 s[4:5], v243, v4
	v_cmp_eq_u32_e64 s[8:9], 0, v5
	v_readlane_b32 s21, v253, 5
	v_cndmask_b32_e64 v5, v174, v243, s[4:5]
	v_lshlrev_b32_e32 v48, 2, v5
	v_and_b32_e32 v5, 8, v2
	v_cmp_eq_u32_e64 s[4:5], 0, v5
	v_cndmask_b32_e64 v5, v174, v242, s[6:7]
	v_cmp_lt_i32_e64 s[6:7], v241, v4
	v_lshlrev_b32_e32 v49, 2, v5
	v_readlane_b32 s22, v253, 6
	v_cndmask_b32_e64 v5, v174, v241, s[6:7]
	v_cmp_lt_i32_e64 s[6:7], v240, v4
	v_readlane_b32 s23, v253, 7
	v_readlane_b32 s24, v253, 8
	v_cndmask_b32_e64 v4, v174, v240, s[6:7]
	v_lshl_add_u32 v44, v2, 4, 0
	v_lshlrev_b32_e32 v50, 2, v5
	v_lshlrev_b32_e32 v51, 2, v4
	v_cmp_gt_i32_e64 s[6:7], 16, v2
	v_lshlrev_b64 v[42:43], 4, v[2:3]
	s_mov_b32 s20, 0xbfb8aa3b
	s_mov_b32 s21, 0x3f2aaaab
	v_mov_b32_e32 v52, 0x3ecc95a3
	s_mov_b32 s22, 0x3f317218
	s_mov_b32 s23, 0x7f800000
	s_mov_b32 s24, 0x33800000
	v_mov_b32_e32 v53, 0x7f800000
	v_mov_b32_e32 v54, 0x7fc00000
	v_mov_b32_e32 v55, 0xff800000
	s_mov_b32 s16, s80
	v_readlane_b32 s17, v253, 1
	v_readlane_b32 s18, v253, 2
	v_readlane_b32 s19, v253, 3
	v_readlane_b32 s25, v253, 9
	v_readlane_b32 s28, v253, 12
	v_readlane_b32 s29, v253, 13
	v_readlane_b32 s30, v253, 14
	v_readlane_b32 s31, v253, 15
	v_readlane_b32 s36, v253, 0
	v_readlane_b32 s37, v253, 1
	v_readlane_b32 s38, v253, 2
	v_readlane_b32 s39, v253, 3
	s_nop 3
	s_mov_b32 s53, s16
	s_add_i32 s54, s53, s78
	s_cmp_lt_i32 s54, 0xc000
	s_cselect_b32 s54, s54, s53
	s_add_i32 s56, s53, 0xffff8000
	s_cmp_lt_i32 s53, 0x8000
	s_cselect_b32 s56, s53, s56
	s_cselect_b32 s89, s37, s39
	s_cselect_b32 s88, s36, s38
	s_lshl_b32 s56, s56, 12
	s_add_u32 s88, s88, s56
	s_addc_u32 s89, s89, 0
	s_add_i32 s57, s54, 0xffff8000
	s_cmp_lt_i32 s54, 0x8000
	s_cselect_b32 s57, s54, s57
	s_cselect_b32 s91, s37, s39
	s_cselect_b32 s90, s36, s38
	s_lshl_b32 s57, s57, 12
	s_add_u32 s90, s90, s57
	s_addc_u32 s91, s91, 0
	global_load_dwordx4 v[26:29], v42, s[88:89]
	global_load_dwordx4 v[22:25], v42, s[88:89] offset:1024
	global_load_dwordx4 v[176:179], v42, s[88:89] offset:2048
	global_load_dwordx4 v[180:183], v42, s[88:89] offset:3072
	global_load_dwordx4 v[30:33], v42, s[90:91]
	global_load_dwordx4 v[18:21], v42, s[90:91] offset:1024
	global_load_dwordx4 v[184:187], v42, s[90:91] offset:2048
	global_load_dwordx4 v[188:191], v42, s[90:91] offset:3072
	s_branch .LBB0_38

.LBB0_38:
	s_add_i32 s25, s16, s78
	s_cmp_lt_i32 s25, 0xc000
	s_cselect_b32 s14, s25, s16
	s_add_i32 s10, s16, 0xffff8000
	s_ashr_i32 s17, s16, 31
	s_cmp_lt_i32 s16, 0x8000
	v_readlane_b32 s36, v253, 0
	s_cselect_b32 s11, s17, 0
	s_cselect_b32 s10, s16, s10
	v_readlane_b32 s37, v253, 1
	v_readlane_b32 s38, v253, 2
	v_readlane_b32 s39, v253, 3
	s_cselect_b32 s15, s37, s39
	s_cselect_b32 s18, s36, s38
	s_lshl_b64 s[10:11], s[10:11], 12
	s_add_u32 s10, s18, s10
	s_addc_u32 s11, s15, s11
	s_waitcnt lgkmcnt(0)
	s_add_i32 s10, s14, 0xffff8000
	s_ashr_i32 s15, s14, 31
	s_cmp_lt_i32 s14, 0x8000
	s_cselect_b32 s11, s15, 0
	s_cselect_b32 s10, s14, s10
	s_cselect_b32 s18, s37, s39
	s_cselect_b32 s19, s36, s38
	s_lshl_b64 s[10:11], s[10:11], 12
	s_add_u32 s10, s19, s10
	s_addc_u32 s11, s18, s11
	s_lshl_b64 s[10:11], s[16:17], 11
	s_lshl_b64 s[18:19], s[14:15], 11
	v_lshl_add_u64 v[34:35], v[40:41], 0, s[10:11]
	v_lshl_add_u64 v[36:37], v[40:41], 0, s[18:19]
	v_readlane_b32 s40, v253, 4
	v_readlane_b32 s41, v253, 5
	v_readlane_b32 s42, v253, 6
	v_readlane_b32 s43, v253, 7
	v_readlane_b32 s44, v253, 8
	v_readlane_b32 s45, v253, 9
	v_readlane_b32 s46, v253, 10
	v_readlane_b32 s47, v253, 11
	v_readlane_b32 s48, v253, 12
	v_readlane_b32 s49, v253, 13
	v_readlane_b32 s50, v253, 14
	v_readlane_b32 s51, v253, 15
	s_waitcnt vmcnt(0)
	v_mov_b64_e32 v[10:11], v[176:177]
	v_mov_b64_e32 v[12:13], v[178:179]
	v_mov_b64_e32 v[2:3], v[180:181]
	v_mov_b64_e32 v[4:5], v[182:183]
	v_mov_b64_e32 v[14:15], v[184:185]
	v_mov_b64_e32 v[16:17], v[186:187]
	v_mov_b64_e32 v[6:7], v[188:189]
	v_mov_b64_e32 v[8:9], v[190:191]
	v_cvt_pk_bf16_f32 v56, v26, v27
	v_cvt_pk_bf16_f32 v57, v28, v29
	s_waitcnt vmcnt(6)
	v_cvt_pk_bf16_f32 v58, v22, v23
	v_cvt_pk_bf16_f32 v59, v24, v25
	s_waitcnt vmcnt(5)
	v_cvt_pk_bf16_f32 v60, v10, v11
	v_cvt_pk_bf16_f32 v61, v12, v13
	s_waitcnt vmcnt(4)
	v_cvt_pk_bf16_f32 v62, v2, v3
	v_cvt_pk_bf16_f32 v63, v4, v5
	global_store_dwordx2 v[34:35], v[56:57], off
	global_store_dwordx2 v[34:35], v[58:59], off offset:512
	global_store_dwordx2 v[34:35], v[60:61], off offset:1024
	global_store_dwordx2 v[34:35], v[62:63], off offset:1536
	s_waitcnt vmcnt(7)
	v_cvt_pk_bf16_f32 v34, v30, v31
	v_cvt_pk_bf16_f32 v35, v32, v33
	s_waitcnt vmcnt(6)
	v_cvt_pk_bf16_f32 v56, v18, v19
	v_cvt_pk_bf16_f32 v57, v20, v21
	s_waitcnt vmcnt(5)
	v_cvt_pk_bf16_f32 v58, v14, v15
	v_cvt_pk_bf16_f32 v59, v16, v17
	s_waitcnt vmcnt(4)
	v_cvt_pk_bf16_f32 v60, v6, v7
	v_cvt_pk_bf16_f32 v61, v8, v9
	global_store_dwordx2 v[36:37], v[34:35], off
	global_store_dwordx2 v[36:37], v[56:57], off offset:512
	global_store_dwordx2 v[36:37], v[58:59], off offset:1024
	global_store_dwordx2 v[36:37], v[60:61], off offset:1536
	ds_read_b128 v[176:179], v44 offset:0
	ds_read_b128 v[180:183], v44 offset:1024
	ds_read_b128 v[184:187], v44 offset:2048
	ds_read_b128 v[188:191], v44 offset:3072
	ds_read_b128 v[192:195], v44 offset:4096
	ds_read_b128 v[196:199], v44 offset:5120
	ds_read_b128 v[200:203], v44 offset:6144
	ds_read_b128 v[204:207], v44 offset:7168
	s_waitcnt lgkmcnt(4)
	v_pk_mul_f32 v[208:209], v[26:27], v[176:177]
	v_pk_mul_f32 v[210:211], v[30:31], v[176:177]
	v_pk_fma_f32 v[208:209], v[28:29], v[178:179], v[208:209]
	v_pk_fma_f32 v[210:211], v[32:33], v[178:179], v[210:211]
	v_pk_fma_f32 v[208:209], v[22:23], v[180:181], v[208:209]
	v_pk_fma_f32 v[210:211], v[18:19], v[180:181], v[210:211]
	v_pk_fma_f32 v[208:209], v[24:25], v[182:183], v[208:209]
	v_pk_fma_f32 v[210:211], v[20:21], v[182:183], v[210:211]
	v_pk_fma_f32 v[208:209], v[10:11], v[184:185], v[208:209]
	v_pk_fma_f32 v[210:211], v[14:15], v[184:185], v[210:211]
	v_pk_fma_f32 v[208:209], v[12:13], v[186:187], v[208:209]
	v_pk_fma_f32 v[210:211], v[16:17], v[186:187], v[210:211]
	v_pk_fma_f32 v[208:209], v[2:3], v[188:189], v[208:209]
	v_pk_fma_f32 v[210:211], v[6:7], v[188:189], v[210:211]
	v_pk_fma_f32 v[208:209], v[4:5], v[190:191], v[208:209]
	v_pk_fma_f32 v[210:211], v[8:9], v[190:191], v[210:211]
	v_add_f32_e32 v142, v208, v209
	v_add_f32_e32 v143, v210, v211
	ds_read_b128 v[176:179], v44 offset:8192
	ds_read_b128 v[180:183], v44 offset:9216
	ds_read_b128 v[184:187], v44 offset:10240
	ds_read_b128 v[188:191], v44 offset:11264
	s_waitcnt lgkmcnt(4)
	v_pk_mul_f32 v[208:209], v[26:27], v[192:193]
	v_pk_mul_f32 v[210:211], v[30:31], v[192:193]
	v_pk_fma_f32 v[208:209], v[28:29], v[194:195], v[208:209]
	v_pk_fma_f32 v[210:211], v[32:33], v[194:195], v[210:211]
	v_pk_fma_f32 v[208:209], v[22:23], v[196:197], v[208:209]
	v_pk_fma_f32 v[210:211], v[18:19], v[196:197], v[210:211]
	v_pk_fma_f32 v[208:209], v[24:25], v[198:199], v[208:209]
	v_pk_fma_f32 v[210:211], v[20:21], v[198:199], v[210:211]
	v_pk_fma_f32 v[208:209], v[10:11], v[200:201], v[208:209]
	v_pk_fma_f32 v[210:211], v[14:15], v[200:201], v[210:211]
	v_pk_fma_f32 v[208:209], v[12:13], v[202:203], v[208:209]
	v_pk_fma_f32 v[210:211], v[16:17], v[202:203], v[210:211]
	v_pk_fma_f32 v[208:209], v[2:3], v[204:205], v[208:209]
	v_pk_fma_f32 v[210:211], v[6:7], v[204:205], v[210:211]
	v_pk_fma_f32 v[208:209], v[4:5], v[206:207], v[208:209]
	v_pk_fma_f32 v[210:211], v[8:9], v[206:207], v[210:211]
	v_add_f32_e32 v144, v208, v209
	v_add_f32_e32 v145, v210, v211
	ds_read_b128 v[192:195], v44 offset:12288
	ds_read_b128 v[196:199], v44 offset:13312
	ds_read_b128 v[200:203], v44 offset:14336
	ds_read_b128 v[204:207], v44 offset:15360
	s_waitcnt lgkmcnt(4)
	v_pk_mul_f32 v[208:209], v[26:27], v[176:177]
	v_pk_mul_f32 v[210:211], v[30:31], v[176:177]
	v_pk_fma_f32 v[208:209], v[28:29], v[178:179], v[208:209]
	v_pk_fma_f32 v[210:211], v[32:33], v[178:179], v[210:211]
	v_pk_fma_f32 v[208:209], v[22:23], v[180:181], v[208:209]
	v_pk_fma_f32 v[210:211], v[18:19], v[180:181], v[210:211]
	v_pk_fma_f32 v[208:209], v[24:25], v[182:183], v[208:209]
	v_pk_fma_f32 v[210:211], v[20:21], v[182:183], v[210:211]
	v_pk_fma_f32 v[208:209], v[10:11], v[184:185], v[208:209]
	v_pk_fma_f32 v[210:211], v[14:15], v[184:185], v[210:211]
	v_pk_fma_f32 v[208:209], v[12:13], v[186:187], v[208:209]
	v_pk_fma_f32 v[210:211], v[16:17], v[186:187], v[210:211]
	v_pk_fma_f32 v[208:209], v[2:3], v[188:189], v[208:209]
	v_pk_fma_f32 v[210:211], v[6:7], v[188:189], v[210:211]
	v_pk_fma_f32 v[208:209], v[4:5], v[190:191], v[208:209]
	v_pk_fma_f32 v[210:211], v[8:9], v[190:191], v[210:211]
	v_add_f32_e32 v146, v208, v209
	v_add_f32_e32 v147, v210, v211
	ds_read_b128 v[176:179], v44 offset:16384
	ds_read_b128 v[180:183], v44 offset:17408
	ds_read_b128 v[184:187], v44 offset:18432
	ds_read_b128 v[188:191], v44 offset:19456
	s_waitcnt lgkmcnt(4)
	v_pk_mul_f32 v[208:209], v[26:27], v[192:193]
	v_pk_mul_f32 v[210:211], v[30:31], v[192:193]
	v_pk_fma_f32 v[208:209], v[28:29], v[194:195], v[208:209]
	v_pk_fma_f32 v[210:211], v[32:33], v[194:195], v[210:211]
	v_pk_fma_f32 v[208:209], v[22:23], v[196:197], v[208:209]
	v_pk_fma_f32 v[210:211], v[18:19], v[196:197], v[210:211]
	v_pk_fma_f32 v[208:209], v[24:25], v[198:199], v[208:209]
	v_pk_fma_f32 v[210:211], v[20:21], v[198:199], v[210:211]
	v_pk_fma_f32 v[208:209], v[10:11], v[200:201], v[208:209]
	v_pk_fma_f32 v[210:211], v[14:15], v[200:201], v[210:211]
	v_pk_fma_f32 v[208:209], v[12:13], v[202:203], v[208:209]
	v_pk_fma_f32 v[210:211], v[16:17], v[202:203], v[210:211]
	v_pk_fma_f32 v[208:209], v[2:3], v[204:205], v[208:209]
	v_pk_fma_f32 v[210:211], v[6:7], v[204:205], v[210:211]
	v_pk_fma_f32 v[208:209], v[4:5], v[206:207], v[208:209]
	v_pk_fma_f32 v[210:211], v[8:9], v[206:207], v[210:211]
	v_add_f32_e32 v148, v208, v209
	v_add_f32_e32 v149, v210, v211
	ds_read_b128 v[192:195], v44 offset:20480
	ds_read_b128 v[196:199], v44 offset:21504
	ds_read_b128 v[200:203], v44 offset:22528
	ds_read_b128 v[204:207], v44 offset:23552
	s_waitcnt lgkmcnt(4)
	v_pk_mul_f32 v[208:209], v[26:27], v[176:177]
	v_pk_mul_f32 v[210:211], v[30:31], v[176:177]
	v_pk_fma_f32 v[208:209], v[28:29], v[178:179], v[208:209]
	v_pk_fma_f32 v[210:211], v[32:33], v[178:179], v[210:211]
	v_pk_fma_f32 v[208:209], v[22:23], v[180:181], v[208:209]
	v_pk_fma_f32 v[210:211], v[18:19], v[180:181], v[210:211]
	v_pk_fma_f32 v[208:209], v[24:25], v[182:183], v[208:209]
	v_pk_fma_f32 v[210:211], v[20:21], v[182:183], v[210:211]
	v_pk_fma_f32 v[208:209], v[10:11], v[184:185], v[208:209]
	v_pk_fma_f32 v[210:211], v[14:15], v[184:185], v[210:211]
	v_pk_fma_f32 v[208:209], v[12:13], v[186:187], v[208:209]
	v_pk_fma_f32 v[210:211], v[16:17], v[186:187], v[210:211]
	v_pk_fma_f32 v[208:209], v[2:3], v[188:189], v[208:209]
	v_pk_fma_f32 v[210:211], v[6:7], v[188:189], v[210:211]
	v_pk_fma_f32 v[208:209], v[4:5], v[190:191], v[208:209]
	v_pk_fma_f32 v[210:211], v[8:9], v[190:191], v[210:211]
	v_add_f32_e32 v150, v208, v209
	v_add_f32_e32 v151, v210, v211
	ds_read_b128 v[176:179], v44 offset:24576
	ds_read_b128 v[180:183], v44 offset:25600
	ds_read_b128 v[184:187], v44 offset:26624
	ds_read_b128 v[188:191], v44 offset:27648
	s_waitcnt lgkmcnt(4)
	v_pk_mul_f32 v[208:209], v[26:27], v[192:193]
	v_pk_mul_f32 v[210:211], v[30:31], v[192:193]
	v_pk_fma_f32 v[208:209], v[28:29], v[194:195], v[208:209]
	v_pk_fma_f32 v[210:211], v[32:33], v[194:195], v[210:211]
	v_pk_fma_f32 v[208:209], v[22:23], v[196:197], v[208:209]
	v_pk_fma_f32 v[210:211], v[18:19], v[196:197], v[210:211]
	v_pk_fma_f32 v[208:209], v[24:25], v[198:199], v[208:209]
	v_pk_fma_f32 v[210:211], v[20:21], v[198:199], v[210:211]
	v_pk_fma_f32 v[208:209], v[10:11], v[200:201], v[208:209]
	v_pk_fma_f32 v[210:211], v[14:15], v[200:201], v[210:211]
	v_pk_fma_f32 v[208:209], v[12:13], v[202:203], v[208:209]
	v_pk_fma_f32 v[210:211], v[16:17], v[202:203], v[210:211]
	v_pk_fma_f32 v[208:209], v[2:3], v[204:205], v[208:209]
	v_pk_fma_f32 v[210:211], v[6:7], v[204:205], v[210:211]
	v_pk_fma_f32 v[208:209], v[4:5], v[206:207], v[208:209]
	v_pk_fma_f32 v[210:211], v[8:9], v[206:207], v[210:211]
	v_add_f32_e32 v152, v208, v209
	v_add_f32_e32 v153, v210, v211
	ds_read_b128 v[192:195], v44 offset:28672
	ds_read_b128 v[196:199], v44 offset:29696
	ds_read_b128 v[200:203], v44 offset:30720
	ds_read_b128 v[204:207], v44 offset:31744
	s_waitcnt lgkmcnt(4)
	v_pk_mul_f32 v[208:209], v[26:27], v[176:177]
	v_pk_mul_f32 v[210:211], v[30:31], v[176:177]
	v_pk_fma_f32 v[208:209], v[28:29], v[178:179], v[208:209]
	v_pk_fma_f32 v[210:211], v[32:33], v[178:179], v[210:211]
	v_pk_fma_f32 v[208:209], v[22:23], v[180:181], v[208:209]
	v_pk_fma_f32 v[210:211], v[18:19], v[180:181], v[210:211]
	v_pk_fma_f32 v[208:209], v[24:25], v[182:183], v[208:209]
	v_pk_fma_f32 v[210:211], v[20:21], v[182:183], v[210:211]
	v_pk_fma_f32 v[208:209], v[10:11], v[184:185], v[208:209]
	v_pk_fma_f32 v[210:211], v[14:15], v[184:185], v[210:211]
	v_pk_fma_f32 v[208:209], v[12:13], v[186:187], v[208:209]
	v_pk_fma_f32 v[210:211], v[16:17], v[186:187], v[210:211]
	v_pk_fma_f32 v[208:209], v[2:3], v[188:189], v[208:209]
	v_pk_fma_f32 v[210:211], v[6:7], v[188:189], v[210:211]
	v_pk_fma_f32 v[208:209], v[4:5], v[190:191], v[208:209]
	v_pk_fma_f32 v[210:211], v[8:9], v[190:191], v[210:211]
	v_add_f32_e32 v154, v208, v209
	v_add_f32_e32 v155, v210, v211
	ds_read_b128 v[176:179], v44 offset:32768
	ds_read_b128 v[180:183], v44 offset:33792
	ds_read_b128 v[184:187], v44 offset:34816
	ds_read_b128 v[188:191], v44 offset:35840
	s_waitcnt lgkmcnt(4)
	v_pk_mul_f32 v[208:209], v[26:27], v[192:193]
	v_pk_mul_f32 v[210:211], v[30:31], v[192:193]
	v_pk_fma_f32 v[208:209], v[28:29], v[194:195], v[208:209]
	v_pk_fma_f32 v[210:211], v[32:33], v[194:195], v[210:211]
	v_pk_fma_f32 v[208:209], v[22:23], v[196:197], v[208:209]
	v_pk_fma_f32 v[210:211], v[18:19], v[196:197], v[210:211]
	v_pk_fma_f32 v[208:209], v[24:25], v[198:199], v[208:209]
	v_pk_fma_f32 v[210:211], v[20:21], v[198:199], v[210:211]
	v_pk_fma_f32 v[208:209], v[10:11], v[200:201], v[208:209]
	v_pk_fma_f32 v[210:211], v[14:15], v[200:201], v[210:211]
	v_pk_fma_f32 v[208:209], v[12:13], v[202:203], v[208:209]
	v_pk_fma_f32 v[210:211], v[16:17], v[202:203], v[210:211]
	v_pk_fma_f32 v[208:209], v[2:3], v[204:205], v[208:209]
	v_pk_fma_f32 v[210:211], v[6:7], v[204:205], v[210:211]
	v_pk_fma_f32 v[208:209], v[4:5], v[206:207], v[208:209]
	v_pk_fma_f32 v[210:211], v[8:9], v[206:207], v[210:211]
	v_add_f32_e32 v156, v208, v209
	v_add_f32_e32 v157, v210, v211
	ds_read_b128 v[192:195], v44 offset:36864
	ds_read_b128 v[196:199], v44 offset:37888
	ds_read_b128 v[200:203], v44 offset:38912
	ds_read_b128 v[204:207], v44 offset:39936
	s_waitcnt lgkmcnt(4)
	v_pk_mul_f32 v[208:209], v[26:27], v[176:177]
	v_pk_mul_f32 v[210:211], v[30:31], v[176:177]
	v_pk_fma_f32 v[208:209], v[28:29], v[178:179], v[208:209]
	v_pk_fma_f32 v[210:211], v[32:33], v[178:179], v[210:211]
	v_pk_fma_f32 v[208:209], v[22:23], v[180:181], v[208:209]
	v_pk_fma_f32 v[210:211], v[18:19], v[180:181], v[210:211]
	v_pk_fma_f32 v[208:209], v[24:25], v[182:183], v[208:209]
	v_pk_fma_f32 v[210:211], v[20:21], v[182:183], v[210:211]
	v_pk_fma_f32 v[208:209], v[10:11], v[184:185], v[208:209]
	v_pk_fma_f32 v[210:211], v[14:15], v[184:185], v[210:211]
	v_pk_fma_f32 v[208:209], v[12:13], v[186:187], v[208:209]
	v_pk_fma_f32 v[210:211], v[16:17], v[186:187], v[210:211]
	v_pk_fma_f32 v[208:209], v[2:3], v[188:189], v[208:209]
	v_pk_fma_f32 v[210:211], v[6:7], v[188:189], v[210:211]
	v_pk_fma_f32 v[208:209], v[4:5], v[190:191], v[208:209]
	v_pk_fma_f32 v[210:211], v[8:9], v[190:191], v[210:211]
	v_add_f32_e32 v158, v208, v209
	v_add_f32_e32 v159, v210, v211
	ds_read_b128 v[176:179], v44 offset:40960
	ds_read_b128 v[180:183], v44 offset:41984
	ds_read_b128 v[184:187], v44 offset:43008
	ds_read_b128 v[188:191], v44 offset:44032
	s_waitcnt lgkmcnt(4)
	v_pk_mul_f32 v[208:209], v[26:27], v[192:193]
	v_pk_mul_f32 v[210:211], v[30:31], v[192:193]
	v_pk_fma_f32 v[208:209], v[28:29], v[194:195], v[208:209]
	v_pk_fma_f32 v[210:211], v[32:33], v[194:195], v[210:211]
	v_pk_fma_f32 v[208:209], v[22:23], v[196:197], v[208:209]
	v_pk_fma_f32 v[210:211], v[18:19], v[196:197], v[210:211]
	v_pk_fma_f32 v[208:209], v[24:25], v[198:199], v[208:209]
	v_pk_fma_f32 v[210:211], v[20:21], v[198:199], v[210:211]
	v_pk_fma_f32 v[208:209], v[10:11], v[200:201], v[208:209]
	v_pk_fma_f32 v[210:211], v[14:15], v[200:201], v[210:211]
	v_pk_fma_f32 v[208:209], v[12:13], v[202:203], v[208:209]
	v_pk_fma_f32 v[210:211], v[16:17], v[202:203], v[210:211]
	v_pk_fma_f32 v[208:209], v[2:3], v[204:205], v[208:209]
	v_pk_fma_f32 v[210:211], v[6:7], v[204:205], v[210:211]
	v_pk_fma_f32 v[208:209], v[4:5], v[206:207], v[208:209]
	v_pk_fma_f32 v[210:211], v[8:9], v[206:207], v[210:211]
	v_add_f32_e32 v160, v208, v209
	v_add_f32_e32 v161, v210, v211
	ds_read_b128 v[192:195], v44 offset:45056
	ds_read_b128 v[196:199], v44 offset:46080
	ds_read_b128 v[200:203], v44 offset:47104
	ds_read_b128 v[204:207], v44 offset:48128
	s_waitcnt lgkmcnt(4)
	v_pk_mul_f32 v[208:209], v[26:27], v[176:177]
	v_pk_mul_f32 v[210:211], v[30:31], v[176:177]
	v_pk_fma_f32 v[208:209], v[28:29], v[178:179], v[208:209]
	v_pk_fma_f32 v[210:211], v[32:33], v[178:179], v[210:211]
	v_pk_fma_f32 v[208:209], v[22:23], v[180:181], v[208:209]
	v_pk_fma_f32 v[210:211], v[18:19], v[180:181], v[210:211]
	v_pk_fma_f32 v[208:209], v[24:25], v[182:183], v[208:209]
	v_pk_fma_f32 v[210:211], v[20:21], v[182:183], v[210:211]
	v_pk_fma_f32 v[208:209], v[10:11], v[184:185], v[208:209]
	v_pk_fma_f32 v[210:211], v[14:15], v[184:185], v[210:211]
	v_pk_fma_f32 v[208:209], v[12:13], v[186:187], v[208:209]
	v_pk_fma_f32 v[210:211], v[16:17], v[186:187], v[210:211]
	v_pk_fma_f32 v[208:209], v[2:3], v[188:189], v[208:209]
	v_pk_fma_f32 v[210:211], v[6:7], v[188:189], v[210:211]
	v_pk_fma_f32 v[208:209], v[4:5], v[190:191], v[208:209]
	v_pk_fma_f32 v[210:211], v[8:9], v[190:191], v[210:211]
	v_add_f32_e32 v162, v208, v209
	v_add_f32_e32 v163, v210, v211
	ds_read_b128 v[176:179], v44 offset:49152
	ds_read_b128 v[180:183], v44 offset:50176
	ds_read_b128 v[184:187], v44 offset:51200
	ds_read_b128 v[188:191], v44 offset:52224
	s_waitcnt lgkmcnt(4)
	v_pk_mul_f32 v[208:209], v[26:27], v[192:193]
	v_pk_mul_f32 v[210:211], v[30:31], v[192:193]
	v_pk_fma_f32 v[208:209], v[28:29], v[194:195], v[208:209]
	v_pk_fma_f32 v[210:211], v[32:33], v[194:195], v[210:211]
	v_pk_fma_f32 v[208:209], v[22:23], v[196:197], v[208:209]
	v_pk_fma_f32 v[210:211], v[18:19], v[196:197], v[210:211]
	v_pk_fma_f32 v[208:209], v[24:25], v[198:199], v[208:209]
	v_pk_fma_f32 v[210:211], v[20:21], v[198:199], v[210:211]
	v_pk_fma_f32 v[208:209], v[10:11], v[200:201], v[208:209]
	v_pk_fma_f32 v[210:211], v[14:15], v[200:201], v[210:211]
	v_pk_fma_f32 v[208:209], v[12:13], v[202:203], v[208:209]
	v_pk_fma_f32 v[210:211], v[16:17], v[202:203], v[210:211]
	v_pk_fma_f32 v[208:209], v[2:3], v[204:205], v[208:209]
	v_pk_fma_f32 v[210:211], v[6:7], v[204:205], v[210:211]
	v_pk_fma_f32 v[208:209], v[4:5], v[206:207], v[208:209]
	v_pk_fma_f32 v[210:211], v[8:9], v[206:207], v[210:211]
	v_add_f32_e32 v164, v208, v209
	v_add_f32_e32 v165, v210, v211
	ds_read_b128 v[192:195], v44 offset:53248
	ds_read_b128 v[196:199], v44 offset:54272
	ds_read_b128 v[200:203], v44 offset:55296
	ds_read_b128 v[204:207], v44 offset:56320
	s_waitcnt lgkmcnt(4)
	v_pk_mul_f32 v[208:209], v[26:27], v[176:177]
	v_pk_mul_f32 v[210:211], v[30:31], v[176:177]
	v_pk_fma_f32 v[208:209], v[28:29], v[178:179], v[208:209]
	v_pk_fma_f32 v[210:211], v[32:33], v[178:179], v[210:211]
	v_pk_fma_f32 v[208:209], v[22:23], v[180:181], v[208:209]
	v_pk_fma_f32 v[210:211], v[18:19], v[180:181], v[210:211]
	v_pk_fma_f32 v[208:209], v[24:25], v[182:183], v[208:209]
	v_pk_fma_f32 v[210:211], v[20:21], v[182:183], v[210:211]
	v_pk_fma_f32 v[208:209], v[10:11], v[184:185], v[208:209]
	v_pk_fma_f32 v[210:211], v[14:15], v[184:185], v[210:211]
	v_pk_fma_f32 v[208:209], v[12:13], v[186:187], v[208:209]
	v_pk_fma_f32 v[210:211], v[16:17], v[186:187], v[210:211]
	v_pk_fma_f32 v[208:209], v[2:3], v[188:189], v[208:209]
	v_pk_fma_f32 v[210:211], v[6:7], v[188:189], v[210:211]
	v_pk_fma_f32 v[208:209], v[4:5], v[190:191], v[208:209]
	v_pk_fma_f32 v[210:211], v[8:9], v[190:191], v[210:211]
	v_add_f32_e32 v166, v208, v209
	v_add_f32_e32 v167, v210, v211
	ds_read_b128 v[176:179], v44 offset:57344
	ds_read_b128 v[180:183], v44 offset:58368
	ds_read_b128 v[184:187], v44 offset:59392
	ds_read_b128 v[188:191], v44 offset:60416
	s_waitcnt lgkmcnt(4)
	v_pk_mul_f32 v[208:209], v[26:27], v[192:193]
	v_pk_mul_f32 v[210:211], v[30:31], v[192:193]
	v_pk_fma_f32 v[208:209], v[28:29], v[194:195], v[208:209]
	v_pk_fma_f32 v[210:211], v[32:33], v[194:195], v[210:211]
	v_pk_fma_f32 v[208:209], v[22:23], v[196:197], v[208:209]
	v_pk_fma_f32 v[210:211], v[18:19], v[196:197], v[210:211]
	v_pk_fma_f32 v[208:209], v[24:25], v[198:199], v[208:209]
	v_pk_fma_f32 v[210:211], v[20:21], v[198:199], v[210:211]
	v_pk_fma_f32 v[208:209], v[10:11], v[200:201], v[208:209]
	v_pk_fma_f32 v[210:211], v[14:15], v[200:201], v[210:211]
	v_pk_fma_f32 v[208:209], v[12:13], v[202:203], v[208:209]
	v_pk_fma_f32 v[210:211], v[16:17], v[202:203], v[210:211]
	v_pk_fma_f32 v[208:209], v[2:3], v[204:205], v[208:209]
	v_pk_fma_f32 v[210:211], v[6:7], v[204:205], v[210:211]
	v_pk_fma_f32 v[208:209], v[4:5], v[206:207], v[208:209]
	v_pk_fma_f32 v[210:211], v[8:9], v[206:207], v[210:211]
	v_add_f32_e32 v168, v208, v209
	v_add_f32_e32 v169, v210, v211
	ds_read_b128 v[192:195], v44 offset:61440
	ds_read_b128 v[196:199], v44 offset:62464
	ds_read_b128 v[200:203], v44 offset:63488
	ds_read_b128 v[204:207], v44 offset:64512
	s_waitcnt lgkmcnt(4)
	v_pk_mul_f32 v[208:209], v[26:27], v[176:177]
	v_pk_mul_f32 v[210:211], v[30:31], v[176:177]
	v_pk_fma_f32 v[208:209], v[28:29], v[178:179], v[208:209]
	v_pk_fma_f32 v[210:211], v[32:33], v[178:179], v[210:211]
	v_pk_fma_f32 v[208:209], v[22:23], v[180:181], v[208:209]
	v_pk_fma_f32 v[210:211], v[18:19], v[180:181], v[210:211]
	v_pk_fma_f32 v[208:209], v[24:25], v[182:183], v[208:209]
	v_pk_fma_f32 v[210:211], v[20:21], v[182:183], v[210:211]
	v_pk_fma_f32 v[208:209], v[10:11], v[184:185], v[208:209]
	v_pk_fma_f32 v[210:211], v[14:15], v[184:185], v[210:211]
	v_pk_fma_f32 v[208:209], v[12:13], v[186:187], v[208:209]
	v_pk_fma_f32 v[210:211], v[16:17], v[186:187], v[210:211]
	v_pk_fma_f32 v[208:209], v[2:3], v[188:189], v[208:209]
	v_pk_fma_f32 v[210:211], v[6:7], v[188:189], v[210:211]
	v_pk_fma_f32 v[208:209], v[4:5], v[190:191], v[208:209]
	v_pk_fma_f32 v[210:211], v[8:9], v[190:191], v[210:211]
	v_add_f32_e32 v170, v208, v209
	v_add_f32_e32 v171, v210, v211
	s_waitcnt lgkmcnt(0)
	v_pk_mul_f32 v[208:209], v[26:27], v[192:193]
	v_pk_mul_f32 v[210:211], v[30:31], v[192:193]
	v_pk_fma_f32 v[208:209], v[28:29], v[194:195], v[208:209]
	v_pk_fma_f32 v[210:211], v[32:33], v[194:195], v[210:211]
	v_pk_fma_f32 v[208:209], v[22:23], v[196:197], v[208:209]
	v_pk_fma_f32 v[210:211], v[18:19], v[196:197], v[210:211]
	v_pk_fma_f32 v[208:209], v[24:25], v[198:199], v[208:209]
	v_pk_fma_f32 v[210:211], v[20:21], v[198:199], v[210:211]
	v_pk_fma_f32 v[208:209], v[10:11], v[200:201], v[208:209]
	v_pk_fma_f32 v[210:211], v[14:15], v[200:201], v[210:211]
	v_pk_fma_f32 v[208:209], v[12:13], v[202:203], v[208:209]
	v_pk_fma_f32 v[210:211], v[16:17], v[202:203], v[210:211]
	v_pk_fma_f32 v[208:209], v[2:3], v[204:205], v[208:209]
	v_pk_fma_f32 v[210:211], v[6:7], v[204:205], v[210:211]
	v_pk_fma_f32 v[208:209], v[4:5], v[206:207], v[208:209]
	v_pk_fma_f32 v[210:211], v[8:9], v[206:207], v[210:211]
	v_add_f32_e32 v172, v208, v209
	v_add_f32_e32 v173, v210, v211
	s_add_i32 s53, s25, s78
	s_cmp_lt_i32 s53, 0xc000
	s_cselect_b32 s53, s53, s16
	s_add_i32 s54, s53, s78
	s_cmp_lt_i32 s54, 0xc000
	s_cselect_b32 s54, s54, s53
	s_add_i32 s56, s53, 0xffff8000
	s_cmp_lt_i32 s53, 0x8000
	s_cselect_b32 s56, s53, s56
	s_cselect_b32 s89, s37, s39
	s_cselect_b32 s88, s36, s38
	s_lshl_b32 s56, s56, 12
	s_add_u32 s88, s88, s56
	s_addc_u32 s89, s89, 0
	s_add_i32 s57, s54, 0xffff8000
	s_cmp_lt_i32 s54, 0x8000
	s_cselect_b32 s57, s54, s57
	s_cselect_b32 s91, s37, s39
	s_cselect_b32 s90, s36, s38
	s_lshl_b32 s57, s57, 12
	s_add_u32 s90, s90, s57
	s_addc_u32 s91, s91, 0
	global_load_dwordx4 v[26:29], v42, s[88:89]
	global_load_dwordx4 v[22:25], v42, s[88:89] offset:1024
	global_load_dwordx4 v[176:179], v42, s[88:89] offset:2048
	global_load_dwordx4 v[180:183], v42, s[88:89] offset:3072
	global_load_dwordx4 v[30:33], v42, s[90:91]
	global_load_dwordx4 v[18:21], v42, s[90:91] offset:1024
	global_load_dwordx4 v[184:187], v42, s[90:91] offset:2048
	global_load_dwordx4 v[188:191], v42, s[90:91] offset:3072
	v_cndmask_b32_e32 v4, v142, v158, vcc
	ds_bpermute_b32 v4, v46, v4
	v_cndmask_b32_e32 v6, v144, v160, vcc
	ds_bpermute_b32 v6, v46, v6
	v_cndmask_b32_e32 v7, v146, v162, vcc
	ds_bpermute_b32 v7, v46, v7
	v_cndmask_b32_e32 v5, v158, v142, vcc
	s_waitcnt lgkmcnt(2)
	v_add_f32_e32 v4, v5, v4
	v_cndmask_b32_e32 v5, v160, v144, vcc
	s_waitcnt lgkmcnt(1)
	v_add_f32_e32 v5, v5, v6
	v_cndmask_b32_e32 v6, v162, v146, vcc
	s_waitcnt lgkmcnt(0)
	v_add_f32_e32 v6, v6, v7
	v_cndmask_b32_e32 v7, v148, v164, vcc
	ds_bpermute_b32 v7, v46, v7
	v_cndmask_b32_e32 v9, v150, v166, vcc
	ds_bpermute_b32 v9, v46, v9
	v_cndmask_b32_e32 v10, v152, v168, vcc
	ds_bpermute_b32 v10, v46, v10
	v_cndmask_b32_e32 v8, v164, v148, vcc
	s_waitcnt lgkmcnt(2)
	v_add_f32_e32 v7, v8, v7
	v_cndmask_b32_e32 v8, v166, v150, vcc
	s_waitcnt lgkmcnt(1)
	v_add_f32_e32 v8, v8, v9
	v_cndmask_b32_e32 v9, v168, v152, vcc
	v_cndmask_b32_e32 v13, v156, v172, vcc
	s_waitcnt lgkmcnt(0)
	v_add_f32_e32 v9, v9, v10
	v_cndmask_b32_e32 v10, v154, v170, vcc
	ds_bpermute_b32 v13, v46, v13
	ds_bpermute_b32 v10, v46, v10
	v_cndmask_b32_e32 v2, v172, v156, vcc
	v_cndmask_b32_e32 v12, v170, v154, vcc
	s_waitcnt lgkmcnt(1)
	v_add_f32_e32 v2, v2, v13
	v_cndmask_b32_e64 v14, v4, v8, s[0:1]
	s_waitcnt lgkmcnt(0)
	v_add_f32_e32 v10, v12, v10
	v_cndmask_b32_e64 v4, v8, v4, s[0:1]
	v_cndmask_b32_e64 v8, v5, v9, s[0:1]
	v_cndmask_b32_e64 v12, v7, v2, s[0:1]
	ds_bpermute_b32 v8, v47, v8
	ds_bpermute_b32 v12, v47, v12
	v_cndmask_b32_e64 v5, v9, v5, s[0:1]
	v_cndmask_b32_e64 v9, v6, v10, s[0:1]
	ds_bpermute_b32 v14, v47, v14
	ds_bpermute_b32 v9, v47, v9
	v_cndmask_b32_e64 v2, v2, v7, s[0:1]
	s_waitcnt lgkmcnt(3)
	v_add_f32_e32 v5, v5, v8
	s_waitcnt lgkmcnt(2)
	v_add_f32_e32 v2, v2, v12
	v_cndmask_b32_e64 v8, v5, v2, s[8:9]
	ds_bpermute_b32 v8, v48, v8
	v_cndmask_b32_e64 v6, v10, v6, s[0:1]
	s_waitcnt lgkmcnt(2)
	v_add_f32_e32 v4, v4, v14
	s_waitcnt lgkmcnt(1)
	v_add_f32_e32 v6, v6, v9
	v_cndmask_b32_e64 v7, v4, v6, s[8:9]
	ds_bpermute_b32 v7, v48, v7
	v_cndmask_b32_e64 v4, v6, v4, s[8:9]
	v_cndmask_b32_e64 v2, v2, v5, s[8:9]
	v_cndmask_b32_e32 v6, v143, v159, vcc
	s_waitcnt lgkmcnt(1)
	v_add_f32_e32 v2, v2, v8
	ds_bpermute_b32 v6, v46, v6
	v_cndmask_b32_e32 v8, v145, v161, vcc
	ds_bpermute_b32 v8, v46, v8
	v_cndmask_b32_e32 v9, v147, v163, vcc
	ds_bpermute_b32 v9, v46, v9
	s_waitcnt lgkmcnt(3)
	v_add_f32_e32 v4, v4, v7
	v_cndmask_b32_e32 v7, v159, v143, vcc
	s_waitcnt lgkmcnt(2)
	v_add_f32_e32 v6, v7, v6
	v_cndmask_b32_e32 v7, v161, v145, vcc
	s_waitcnt lgkmcnt(1)
	v_add_f32_e32 v7, v7, v8
	v_cndmask_b32_e32 v8, v163, v147, vcc
	s_waitcnt lgkmcnt(0)
	v_add_f32_e32 v8, v8, v9
	v_cndmask_b32_e32 v9, v149, v165, vcc
	ds_bpermute_b32 v9, v46, v9
	v_cndmask_b32_e32 v11, v151, v167, vcc
	ds_bpermute_b32 v11, v46, v11
	v_cndmask_b32_e32 v12, v153, v169, vcc
	ds_bpermute_b32 v12, v46, v12
	v_cndmask_b32_e32 v10, v165, v149, vcc
	s_waitcnt lgkmcnt(2)
	v_add_f32_e32 v9, v10, v9
	v_cndmask_b32_e32 v10, v167, v151, vcc
	s_waitcnt lgkmcnt(1)
	v_add_f32_e32 v10, v10, v11
	v_cndmask_b32_e32 v11, v169, v153, vcc
	s_waitcnt lgkmcnt(0)
	v_add_f32_e32 v11, v11, v12
	v_cndmask_b32_e32 v12, v155, v171, vcc
	v_cndmask_b32_e32 v14, v157, v173, vcc
	ds_bpermute_b32 v12, v46, v12
	ds_bpermute_b32 v14, v46, v14
	v_cndmask_b32_e32 v13, v171, v155, vcc
	v_cndmask_b32_e32 v3, v173, v157, vcc
	v_cndmask_b32_e64 v15, v6, v10, s[0:1]
	s_waitcnt lgkmcnt(1)
	v_add_f32_e32 v12, v13, v12
	s_waitcnt lgkmcnt(0)
	v_add_f32_e32 v3, v3, v14
	v_cndmask_b32_e64 v6, v10, v6, s[0:1]
	v_cndmask_b32_e64 v10, v7, v11, s[0:1]
	v_cndmask_b32_e64 v7, v11, v7, s[0:1]
	v_cndmask_b32_e64 v11, v8, v12, s[0:1]
	v_cndmask_b32_e64 v13, v9, v3, s[0:1]
	ds_bpermute_b32 v15, v47, v15
	ds_bpermute_b32 v10, v47, v10
	ds_bpermute_b32 v11, v47, v11
	ds_bpermute_b32 v13, v47, v13
	v_cndmask_b32_e64 v8, v12, v8, s[0:1]
	v_cndmask_b32_e64 v3, v3, v9, s[0:1]
	s_waitcnt lgkmcnt(3)
	v_add_f32_e32 v6, v6, v15
	s_waitcnt lgkmcnt(2)
	v_add_f32_e32 v7, v7, v10
	s_waitcnt lgkmcnt(1)
	v_add_f32_e32 v8, v8, v11
	s_waitcnt lgkmcnt(0)
	v_add_f32_e32 v3, v3, v13
	v_cndmask_b32_e64 v9, v6, v8, s[8:9]
	v_cndmask_b32_e64 v10, v7, v3, s[8:9]
	ds_bpermute_b32 v9, v48, v9
	ds_bpermute_b32 v10, v48, v10
	v_cndmask_b32_e64 v6, v8, v6, s[8:9]
	v_cndmask_b32_e64 v3, v3, v7, s[8:9]
	v_cndmask_b32_e64 v5, v4, v2, s[4:5]
	s_waitcnt lgkmcnt(1)
	v_add_f32_e32 v6, v6, v9
	s_waitcnt lgkmcnt(0)
	v_add_f32_e32 v3, v3, v10
	v_cndmask_b32_e64 v7, v6, v3, s[4:5]
	ds_bpermute_b32 v5, v49, v5
	ds_bpermute_b32 v7, v49, v7
	v_cndmask_b32_e64 v2, v2, v4, s[4:5]
	v_cndmask_b32_e64 v3, v3, v6, s[4:5]
	s_waitcnt lgkmcnt(1)
	v_add_f32_e32 v2, v2, v5
	s_waitcnt lgkmcnt(0)
	v_add_f32_e32 v3, v3, v7
	ds_bpermute_b32 v4, v50, v2
	ds_bpermute_b32 v6, v50, v3
	s_waitcnt lgkmcnt(1)
	v_add_f32_e32 v4, v2, v4
	s_waitcnt lgkmcnt(0)
	v_add_f32_e32 v2, v3, v6
	ds_bpermute_b32 v5, v51, v4
	ds_bpermute_b32 v3, v51, v2
	s_and_saveexec_b64 s[18:19], s[6:7]
	s_cbranch_execz .LBB0_37
	s_waitcnt lgkmcnt(1)
	v_add_f32_e32 v4, v4, v5
	v_add_f32_e32 v4, v1, v4
	v_mul_f32_e64 v5, |v4|, s20
	v_exp_f32_e32 v5, v5
	s_waitcnt lgkmcnt(0)
	v_add_f32_e32 v2, v2, v3
	v_add_f32_e32 v6, v1, v2
	v_max_f32_e32 v4, 0, v4
	v_add_f32_e32 v7, 1.0, v5
	v_add_f32_e32 v2, -1.0, v7
	v_sub_f32_e32 v3, v2, v7
	v_add_f32_e32 v3, 1.0, v3
	v_sub_f32_e32 v2, v5, v2
	v_add_f32_e32 v8, v2, v3
	v_frexp_mant_f32_e32 v9, v7
	v_cvt_f64_f32_e32 v[2:3], v7
	v_frexp_exp_i32_f64_e32 v2, v[2:3]
	v_cmp_gt_f32_e64 s[10:11], s21, v9
	s_nop 1
	v_subbrev_co_u32_e64 v2, s[10:11], 0, v2, s[10:11]
	v_sub_u32_e32 v3, 0, v2
	v_ldexp_f32 v7, v7, v3
	v_ldexp_f32 v3, v8, v3
	v_add_f32_e32 v8, -1.0, v7
	v_add_f32_e32 v11, 1.0, v7
	v_add_f32_e32 v9, 1.0, v8
	v_add_f32_e32 v12, -1.0, v11
	v_sub_f32_e32 v9, v7, v9
	v_sub_f32_e32 v7, v7, v12
	v_add_f32_e32 v9, v3, v9
	v_add_f32_e32 v3, v3, v7
	v_add_f32_e32 v7, v11, v3
	v_rcp_f32_e32 v12, v7
	v_add_f32_e32 v10, v8, v9
	v_sub_f32_e32 v8, v10, v8
	v_sub_f32_e32 v8, v9, v8
	v_sub_f32_e32 v9, v7, v11
	v_sub_f32_e32 v3, v3, v9
	v_mul_f32_e32 v9, v10, v12
	v_mul_f32_e32 v11, v7, v9
	v_fma_f32 v13, v9, v7, -v11
	v_fmac_f32_e32 v13, v9, v3
	v_add_f32_e32 v14, v11, v13
	v_sub_f32_e32 v15, v10, v14
	v_sub_f32_e32 v10, v10, v15
	v_sub_f32_e32 v11, v14, v11
	v_sub_f32_e32 v10, v10, v14
	v_add_f32_e32 v8, v8, v10
	v_sub_f32_e32 v10, v11, v13
	v_add_f32_e32 v8, v10, v8
	v_add_f32_e32 v10, v15, v8
	v_mul_f32_e32 v11, v12, v10
	v_mul_f32_e32 v13, v7, v11
	v_fma_f32 v7, v11, v7, -v13
	v_fmac_f32_e32 v7, v11, v3
	v_sub_f32_e32 v3, v15, v10
	v_add_f32_e32 v3, v8, v3
	v_add_f32_e32 v8, v13, v7
	v_sub_f32_e32 v14, v10, v8
	v_sub_f32_e32 v10, v10, v14
	v_sub_f32_e32 v13, v8, v13
	v_sub_f32_e32 v8, v10, v8
	v_add_f32_e32 v3, v3, v8
	v_sub_f32_e32 v7, v13, v7
	v_cvt_f32_i32_e32 v2, v2
	v_add_f32_e32 v3, v7, v3
	v_add_f32_e32 v7, v9, v11
	v_add_f32_e32 v3, v14, v3
	v_sub_f32_e32 v8, v7, v9
	v_mul_f32_e32 v3, v12, v3
	v_sub_f32_e32 v8, v11, v8
	v_add_f32_e32 v3, v8, v3
	v_mul_f32_e32 v11, 0x3f317218, v2
	v_add_f32_e32 v8, v7, v3
	v_fma_f32 v12, v2, s22, -v11
	v_mul_f32_e32 v9, v8, v8
	v_fmac_f32_e32 v12, 0xb102e308, v2
	v_sub_f32_e32 v2, v8, v7
	v_fmamk_f32 v10, v9, 0x3e9b6dac, v52
	v_sub_f32_e32 v2, v3, v2
	v_add_f32_e32 v3, v11, v12
	v_fmaak_f32 v10, v9, v10, 0x3f2aaada
	v_sub_f32_e32 v7, v3, v11
	v_ldexp_f32 v11, v8, 1
	v_mul_f32_e32 v8, v8, v9
	v_mul_f32_e32 v8, v8, v10
	v_add_f32_e32 v9, v11, v8
	v_sub_f32_e32 v10, v9, v11
	v_ldexp_f32 v2, v2, 1
	v_sub_f32_e32 v8, v8, v10
	v_add_f32_e32 v2, v2, v8
	v_add_f32_e32 v8, v9, v2
	v_sub_f32_e32 v9, v8, v9
	v_sub_f32_e32 v2, v2, v9
	v_add_f32_e32 v9, v3, v8
	v_sub_f32_e32 v10, v9, v3
	v_sub_f32_e32 v11, v9, v10
	v_sub_f32_e32 v7, v12, v7
	v_sub_f32_e32 v3, v3, v11
	v_sub_f32_e32 v8, v8, v10
	v_add_f32_e32 v3, v8, v3
	v_add_f32_e32 v8, v7, v2
	v_sub_f32_e32 v10, v8, v7
	v_sub_f32_e32 v11, v8, v10
	v_sub_f32_e32 v7, v7, v11
	v_sub_f32_e32 v2, v2, v10
	v_add_f32_e32 v3, v8, v3
	v_add_f32_e32 v2, v2, v7
	v_add_f32_e32 v7, v9, v3
	v_sub_f32_e32 v8, v7, v9
	v_sub_f32_e32 v3, v3, v8
	v_add_f32_e32 v2, v2, v3
	v_add_f32_e32 v2, v7, v2
	v_cmp_neq_f32_e64 s[10:11], s23, v5
	s_nop 1
	v_cndmask_b32_e64 v2, v53, v2, s[10:11]
	v_cmp_ngt_f32_e64 s[10:11], -1.0, v5
	s_nop 1
	v_cndmask_b32_e64 v2, v54, v2, s[10:11]
	v_cmp_neq_f32_e64 s[10:11], -1.0, v5
	s_nop 1
	v_cndmask_b32_e64 v2, v55, v2, s[10:11]
	v_cmp_lt_f32_e64 s[10:11], |v5|, s24
	s_nop 1
	v_cndmask_b32_e64 v2, v2, v5, s[10:11]
	v_add_f32_e32 v4, v4, v2
	v_mul_f32_e64 v2, |v6|, s20
	v_exp_f32_e32 v5, v2
	s_lshl_b64 s[10:11], s[16:17], 6
	v_lshl_add_u64 v[2:3], v[38:39], 0, s[10:11]
	global_store_dword v[2:3], v4, off
	v_max_f32_e32 v4, 0, v6
	v_add_f32_e32 v6, 1.0, v5
	v_add_f32_e32 v2, -1.0, v6
	v_sub_f32_e32 v3, v2, v6
	v_add_f32_e32 v3, 1.0, v3
	v_sub_f32_e32 v2, v5, v2
	v_add_f32_e32 v7, v2, v3
	v_frexp_mant_f32_e32 v8, v6
	v_cvt_f64_f32_e32 v[2:3], v6
	v_frexp_exp_i32_f64_e32 v2, v[2:3]
	v_cmp_gt_f32_e64 s[10:11], s21, v8
	s_nop 1
	v_subbrev_co_u32_e64 v2, s[10:11], 0, v2, s[10:11]
	v_sub_u32_e32 v3, 0, v2
	v_ldexp_f32 v6, v6, v3
	v_ldexp_f32 v3, v7, v3
	v_add_f32_e32 v7, -1.0, v6
	v_add_f32_e32 v10, 1.0, v6
	v_add_f32_e32 v8, 1.0, v7
	v_add_f32_e32 v11, -1.0, v10
	v_sub_f32_e32 v8, v6, v8
	v_sub_f32_e32 v6, v6, v11
	v_add_f32_e32 v8, v3, v8
	v_add_f32_e32 v3, v3, v6
	v_add_f32_e32 v6, v10, v3
	v_rcp_f32_e32 v11, v6
	v_add_f32_e32 v9, v7, v8
	v_sub_f32_e32 v7, v9, v7
	v_sub_f32_e32 v7, v8, v7
	v_sub_f32_e32 v8, v6, v10
	v_sub_f32_e32 v3, v3, v8
	v_mul_f32_e32 v8, v9, v11
	v_mul_f32_e32 v10, v6, v8
	v_fma_f32 v12, v8, v6, -v10
	v_fmac_f32_e32 v12, v8, v3
	v_add_f32_e32 v13, v10, v12
	v_sub_f32_e32 v14, v9, v13
	v_sub_f32_e32 v9, v9, v14
	v_sub_f32_e32 v10, v13, v10
	v_sub_f32_e32 v9, v9, v13
	v_add_f32_e32 v7, v7, v9
	v_sub_f32_e32 v9, v10, v12
	v_add_f32_e32 v7, v9, v7
	v_add_f32_e32 v9, v14, v7
	v_mul_f32_e32 v10, v11, v9
	v_mul_f32_e32 v12, v6, v10
	v_fma_f32 v6, v10, v6, -v12
	v_fmac_f32_e32 v6, v10, v3
	v_sub_f32_e32 v3, v14, v9
	v_add_f32_e32 v3, v7, v3
	v_add_f32_e32 v7, v12, v6
	v_sub_f32_e32 v13, v9, v7
	v_sub_f32_e32 v9, v9, v13
	v_sub_f32_e32 v12, v7, v12
	v_sub_f32_e32 v7, v9, v7
	v_add_f32_e32 v3, v3, v7
	v_sub_f32_e32 v6, v12, v6
	v_cvt_f32_i32_e32 v2, v2
	v_add_f32_e32 v3, v6, v3
	v_add_f32_e32 v6, v8, v10
	v_add_f32_e32 v3, v13, v3
	v_sub_f32_e32 v7, v6, v8
	v_mul_f32_e32 v3, v11, v3
	v_sub_f32_e32 v7, v10, v7
	v_add_f32_e32 v3, v7, v3
	v_mul_f32_e32 v10, 0x3f317218, v2
	v_add_f32_e32 v7, v6, v3
	v_fma_f32 v11, v2, s22, -v10
	v_mul_f32_e32 v8, v7, v7
	v_fmac_f32_e32 v11, 0xb102e308, v2
	v_sub_f32_e32 v2, v7, v6
	v_fmamk_f32 v9, v8, 0x3e9b6dac, v52
	v_sub_f32_e32 v2, v3, v2
	v_add_f32_e32 v3, v10, v11
	v_fmaak_f32 v9, v8, v9, 0x3f2aaada
	v_sub_f32_e32 v6, v3, v10
	v_ldexp_f32 v10, v7, 1
	v_mul_f32_e32 v7, v7, v8
	v_mul_f32_e32 v7, v7, v9
	v_add_f32_e32 v8, v10, v7
	v_sub_f32_e32 v9, v8, v10
	v_ldexp_f32 v2, v2, 1
	v_sub_f32_e32 v7, v7, v9
	v_add_f32_e32 v2, v2, v7
	v_add_f32_e32 v7, v8, v2
	v_sub_f32_e32 v8, v7, v8
	v_sub_f32_e32 v2, v2, v8
	v_add_f32_e32 v8, v3, v7
	v_sub_f32_e32 v9, v8, v3
	v_sub_f32_e32 v10, v8, v9
	v_sub_f32_e32 v6, v11, v6
	v_sub_f32_e32 v3, v3, v10
	v_sub_f32_e32 v7, v7, v9
	v_add_f32_e32 v3, v7, v3
	v_add_f32_e32 v7, v6, v2
	v_sub_f32_e32 v9, v7, v6
	v_sub_f32_e32 v10, v7, v9
	v_sub_f32_e32 v6, v6, v10
	v_sub_f32_e32 v2, v2, v9
	v_add_f32_e32 v3, v7, v3
	v_add_f32_e32 v2, v2, v6
	v_add_f32_e32 v6, v8, v3
	v_sub_f32_e32 v7, v6, v8
	v_sub_f32_e32 v3, v3, v7
	v_add_f32_e32 v2, v2, v3
	v_add_f32_e32 v2, v6, v2
	v_cmp_neq_f32_e64 s[10:11], s23, v5
	s_nop 1
	v_cndmask_b32_e64 v2, v53, v2, s[10:11]
	v_cmp_ngt_f32_e64 s[10:11], -1.0, v5
	s_nop 1
	v_cndmask_b32_e64 v2, v54, v2, s[10:11]
	v_cmp_neq_f32_e64 s[10:11], -1.0, v5
	s_nop 1
	v_cndmask_b32_e64 v2, v55, v2, s[10:11]
	v_cmp_lt_f32_e64 s[10:11], |v5|, s24
	s_nop 1
	v_cndmask_b32_e64 v2, v2, v5, s[10:11]
	s_lshl_b64 s[10:11], s[14:15], 6
	v_add_f32_e32 v4, v4, v2
	v_lshl_add_u64 v[2:3], v[38:39], 0, s[10:11]
	global_store_dword v[2:3], v4, off
	s_branch .LBB0_37
